# attention: -mrun folded into QK MFMA accumulator init (f32), redundant max/add ops removed; plus upproj zero-block skip
# speedup vs baseline: 1.0168x; 1.0168x over previous
; #define ATT_ISSUE_K(jt, stage) do { _Pragma("unroll") for (int i_ = 0; i_ < 3; ++i_) ATT_DMA(kg + (size_t)(jt) * KTILE + kgo[i_], KRING + (stage) * KTILE + (wave * 3 + i_) * 1024); } while (0)
; __device__ __forceinline__ void attn_unit(LAS unsigned char* lds, const bf16_t* Qg, const bf16_t* Kg, const bf16_t* Vtg, bf16_t* Og, int bh, int qb, int tid_, int wave, int lane_) {
;     int tid = tid_; asm volatile("" : "+v"(tid));
;     const int lane = tid & 63;
;     const int rg = wave & 3, kh = wave >> 2, r = lane & 31, hi = lane >> 5;
;     const int b = bh >> 2, h = bh & 3;
;     const int nt = 2 * (qb + 1);
;     const float NEG = -1e30f;
;     bf16x8 qf[12];
;     { const bf16_t* qp = Qg + ((size_t)bh * SEQ + 128 * qb + 32 * rg + r) * QKD + 8 * hi;
; #pragma unroll
;       for (int kk = 0; kk < 12; ++kk) qf[kk] = *(const bf16x8*)(qp + 16 * kk); }
;     const unsigned char* kg = (const unsigned char*)(Kg + (size_t)bh * SEQ * QKD);
;     const unsigned char* vg = (const unsigned char*)(Vtg + (size_t)bh * VD * SEQ);
;     unsigned kgo[3], vgo[2];
; #pragma unroll
;     for (int i = 0; i < 3; ++i) { const int a = (wave * 3 + i) * 1024 + lane * 16, row = a / 384, cp = (a % 384) >> 4, cl = (cp & ~7) | ((cp ^ (row >> 1)) & 7); kgo[i] = (unsigned)(row * 384 + cl * 16); }
; #pragma unroll
;     for (int i = 0; i < 2; ++i) { const int a = (wave * 2 + i) * 1024 + lane * 16, row = a >> 7, cp = (a & 127) >> 4, cl = (cp ^ (row >> 1)) & 7; vgo[i] = (unsigned)(row * (SEQ * 2) + cl * 16); }
;     const int sw = (r >> 1) & 7;
;     unsigned kro[4], vro[2];
; #pragma unroll
;     for (int q = 0; q < 4; ++q) kro[q] = (unsigned)((32 * kh + r) * 384 + (((2 * q + hi) ^ sw) * 16));
; #pragma unroll
;     for (int s = 0; s < 2; ++s) vro[s] = (unsigned)(VRING + r * 128 + (((4 * kh + 2 * s + hi) ^ sw) * 16));
;     f32x16 o[4]; float mrun = NEG, lrun = 0.f;
; #pragma unroll
;     for (int dt = 0; dt < 4; ++dt)
; #pragma unroll
;         for (int i = 0; i < 16; ++i) o[dt][i] = 0.f;
;     ATT_ISSUE_K(0, 0); ATT_ISSUE_V(0, 0); ATT_ISSUE_K(1, 1);
;     ATT_ISSUE_K((2 < nt) ? 2 : nt - 1, 2); ATT_ISSUE_V(1, 1);
;     asm volatile("s_waitcnt vmcnt(5)" ::: "memory"); __builtin_amdgcn_s_barrier(); asm volatile("" ::: "memory");
.LBB0_475:
	s_ashr_i32 s40, s72, 3
	s_sub_i32 s0, 63, s40
	s_and_b32 s73, s72, 7
	s_lshl_b32 s66, s0, 7
	s_mov_b64 s[8:9], s[88:89]
	s_lshl_b32 s44, s0, 1
	s_lshl_b32 s41, s73, 13
	s_ashr_i32 s88, s66, 31
	v_mov_b32_e32 v4, v254
	s_add_u32 s0, s41, s66
	s_addc_u32 s4, 0, s88
	v_and_b32_e32 v180, 31, v4
	s_or_b32 s0, s0, s97
	v_or_b32_e32 v0, s0, v180
	v_bfe_u32 v24, v4, 5, 1
	v_mad_u64_u32 v[0:1], s[0:1], v0, s61, v[178:179]
	v_mad_i32_i24 v1, s4, v195, v1
	v_lshlrev_b32_e32 v176, 4, v24
	v_and_b32_e32 v181, 63, v4
	v_lshl_add_u64 v[0:1], v[0:1], 0, v[176:177]
	global_load_dwordx4 v[96:99], v[0:1], off
	global_load_dwordx4 v[100:103], v[0:1], off offset:32
	global_load_dwordx4 v[104:107], v[0:1], off offset:64
	global_load_dwordx4 v[108:111], v[0:1], off offset:96
	global_load_dwordx4 v[112:115], v[0:1], off offset:128
	global_load_dwordx4 v[116:119], v[0:1], off offset:160
	global_load_dwordx4 v[120:123], v[0:1], off offset:192
	global_load_dwordx4 v[124:127], v[0:1], off offset:224
	global_load_dwordx4 v[128:131], v[0:1], off offset:256
	global_load_dwordx4 v[132:135], v[0:1], off offset:288
	global_load_dwordx4 v[136:139], v[0:1], off offset:320
	global_load_dwordx4 v[140:143], v[0:1], off offset:352
	v_lshlrev_b32_e32 v0, 4, v181
	v_or_b32_e32 v1, s59, v0
	v_mul_hi_i32 v2, v1, s42
	v_lshrrev_b32_e32 v3, 31, v2
	v_ashrrev_i32_e32 v2, 6, v2
	v_add_u32_e32 v2, v2, v3
	v_mul_i32_i24_e32 v3, 0x180, v2
	v_lshlrev_b32_e32 v2, 3, v2
	v_sub_u32_e32 v1, v1, v3
	v_and_b32_e32 v2, 0x70, v2
	v_xad_u32 v176, v2, v1, v3
	v_or_b32_e32 v1, s60, v0
	v_mul_hi_i32 v2, v1, s42
	v_lshrrev_b32_e32 v3, 31, v2
	v_ashrrev_i32_e32 v2, 6, v2
	v_add_u32_e32 v2, v2, v3
	v_mul_i32_i24_e32 v3, 0x180, v2
	v_lshlrev_b32_e32 v2, 3, v2
	v_sub_u32_e32 v1, v1, v3
	v_and_b32_e32 v2, 0x70, v2
	v_xad_u32 v182, v2, v1, v3
	v_or_b32_e32 v1, s67, v0
	v_mul_hi_i32 v2, v1, s42
	v_lshrrev_b32_e32 v3, 31, v2
	v_ashrrev_i32_e32 v2, 6, v2
	v_add_u32_e32 v2, v2, v3
	v_mul_i32_i24_e32 v3, 0x180, v2
	v_lshlrev_b32_e32 v2, 3, v2
	s_mul_i32 s0, s73, 0x300000
	s_lshl_b32 s1, s73, 21
	v_sub_u32_e32 v1, v1, v3
	v_and_b32_e32 v2, 0x70, v2
	v_readlane_b32 s4, v255, 32
	v_xad_u32 v184, v2, v1, v3
	v_readlane_b32 s5, v255, 33
	s_add_u32 s92, s4, s0
	v_or_b32_e32 v0, s68, v0
	v_lshlrev_b32_e32 v2, 4, v4
	v_and_b32_e32 v3, 48, v4
	s_mov_b32 m0, s71
	s_addc_u32 s93, s5, 0
	v_lshlrev_b32_e32 v1, 7, v0
	v_bitop3_b32 v2, v2, v3, s86 bitop3:0x6c
	v_or_b32_e32 v0, 0x400, v0
	v_and_or_b32 v186, v1, s62, v2
	v_lshrrev_b32_e32 v1, 8, v0
	s_add_i32 s89, s44, 2
	global_load_lds_dwordx4 v176, s[92:93]
	s_mov_b32 m0, s91
	v_readlane_b32 s0, v255, 52
	v_xor_b32_e32 v1, v1, v4
	v_lshlrev_b32_e32 v0, 7, v0
	global_load_lds_dwordx4 v182, s[92:93]
	s_mov_b32 m0, s74
	s_add_u32 s94, s0, s1
	v_readlane_b32 s0, v255, 53
	v_and_b32_e32 v0, 0xffffc000, v0
	v_lshlrev_b32_e32 v1, 4, v1
	global_load_lds_dwordx4 v184, s[92:93]
	s_addc_u32 s95, s0, 0
	s_mov_b32 m0, s96
	v_and_or_b32 v188, v1, s86, v0
	global_load_lds_dwordx4 v186, s[94:95]
	s_mov_b32 m0, s43
	s_add_u32 s38, s92, 0x6000
	global_load_lds_dwordx4 v188, s[94:95]
	s_addc_u32 s39, s93, 0
	s_mov_b32 m0, s75
	s_or_b32 s45, s44, 1
	global_load_lds_dwordx4 v176, s[38:39]
	s_mov_b32 m0, s90
	s_add_u32 s0, s92, 0xc000
	global_load_lds_dwordx4 v182, s[38:39]
	s_mov_b32 m0, s2
	s_addc_u32 s1, s93, 0
	global_load_lds_dwordx4 v184, s[38:39]
	s_mov_b32 m0, s85
	v_mov_b32_e32 v187, v177
	global_load_lds_dwordx4 v176, s[0:1]
	s_mov_b32 m0, s87
	v_lshl_add_u64 v[0:1], s[94:95], 0, v[186:187]
	v_mov_b32_e32 v189, v177
	global_load_lds_dwordx4 v182, s[0:1]
	s_mov_b32 m0, s3
	v_lshl_add_u64 v[2:3], s[94:95], 0, v[188:189]
	global_load_lds_dwordx4 v184, s[0:1]
	v_lshl_add_u64 v[0:1], v[0:1], 0, s[78:79]
	s_mov_b32 m0, s33
	v_or_b32_e32 v5, s70, v24
	global_load_lds_dwordx4 v[0:1], off
	v_lshl_add_u64 v[0:1], v[2:3], 0, s[78:79]
	s_mov_b32 m0, s10
	s_mov_b32 s48, s49
	global_load_lds_dwordx4 v[0:1], off
	v_lshrrev_b32_e32 v0, 1, v4
	v_or_b32_e32 v1, s69, v180
	v_bfe_u32 v4, v4, 1, 3
	v_mul_lo_u32 v1, v1, s61
	v_bitop3_b32 v0, v24, v0, 7 bitop3:0x78
	v_lshl_or_b32 v191, v0, 4, v1
	v_bitop3_b32 v0, v24, v4, 2 bitop3:0x36
	v_lshl_or_b32 v197, v0, 4, v1
	v_bitop3_b32 v0, v24, v4, 4 bitop3:0x36
	v_lshl_or_b32 v199, v0, 4, v1
	v_bitop3_b32 v0, v24, v4, 6 bitop3:0x36
	s_waitcnt vmcnt(5)
	s_barrier
; #define LAS __attribute__((address_space(3)))
; #define MFMA32(a, b, c) __builtin_amdgcn_mfma_f32_32x32x16_bf16((a), (b), (c), 0, 0, 0)
; #define ATT_ISSUE_K(jt, stage) do { _Pragma("unroll") for (int i_ = 0; i_ < 3; ++i_) ATT_DMA(kg + (size_t)(jt) * KTILE + kgo[i_], KRING + (stage) * KTILE + (wave * 3 + i_) * 1024); } while (0)
; #define ATT_ISSUE_V(jt, stage) do { _Pragma("unroll") for (int i_ = 0; i_ < 2; ++i_) ATT_DMA(vg + (size_t)(jt) * 128 + vgo[i_], VRING + (stage) * VTILE + (wave * 2 + i_) * 1024); } while (0)
; __device__ __forceinline__ void attn_unit(LAS unsigned char* lds, const bf16_t* Qg, const bf16_t* Kg, const bf16_t* Vtg, bf16_t* Og, int bh, int qb, int tid_, int wave, int lane_) {
;     ...
;     f32x16 o[4]; float mrun = NEG, lrun = 0.f;
; #pragma unroll
;     for (int dt = 0; dt < 4; ++dt)
; #pragma unroll
;         for (int i = 0; i < 16; ++i) o[dt][i] = 0.f;
;     ATT_ISSUE_K(0, 0); ATT_ISSUE_V(0, 0); ATT_ISSUE_K(1, 1);
;     ATT_ISSUE_K((2 < nt) ? 2 : nt - 1, 2); ATT_ISSUE_V(1, 1);
;     asm volatile("s_waitcnt vmcnt(5)" ::: "memory"); __builtin_amdgcn_s_barrier(); asm volatile("" ::: "memory");
;     f32x16 sc, sn;
;     {
; #pragma unroll
;       for (int i = 0; i < 16; ++i) sc[i] = 0.f;
; #pragma unroll
;       for (int kk = 0; kk < 12; ++kk) { const bf16x8 kf = *(const LAS bf16x8*)(lds + KRING + kro[kk & 3] + (kk >> 2) * 128); sc = MFMA32(kf, qf[kk], sc); if ((kk & 3) == 3) __builtin_amdgcn_sched_barrier(0); } }
;     asm volatile("s_waitcnt lgkmcnt(0)" ::: "memory"); __builtin_amdgcn_s_barrier(); asm volatile("" ::: "memory");
;     const float NINF = -__builtin_inff();
;     int s0 = 0, s1 = 1, s2 = 2;
	v_add_u32_e32 v25, 0, v191
	v_lshl_or_b32 v200, v0, 4, v1
	ds_read_b128 v[0:3], v25
	v_bitop3_b32 v6, v24, v4, s70 bitop3:0x36
	v_bitop3_b32 v4, v5, v4, 2 bitop3:0x36
	v_add_u32_e32 v26, 0, v197
	v_lshlrev_b32_e32 v201, 4, v6
	v_lshlrev_b32_e32 v202, 4, v4
	ds_read_b128 v[4:7], v26
	s_waitcnt vmcnt(0) lgkmcnt(0)
	v_mfma_f32_32x32x16_bf16 v[64:79], v[0:3], v[96:99], 0
	v_add_u32_e32 v27, 0, v199
	ds_read_b128 v[0:3], v27
	v_add_u32_e32 v28, 0, v200
	ds_read_b128 v[16:19], v28
	s_mov_b32 s50, s49
	s_mov_b32 s51, s49
	s_mov_b32 s52, s49
	v_mfma_f32_32x32x16_bf16 v[64:79], v[4:7], v[100:103], v[64:79]
	s_mov_b32 s53, s49
	s_mov_b32 s54, s49
	s_mov_b32 s55, s49
	s_mov_b32 s56, s49
	s_mov_b32 s57, s49
	s_mov_b32 s58, s49
	s_mov_b32 s0, s59
	s_waitcnt lgkmcnt(1)
	v_mfma_f32_32x32x16_bf16 v[64:79], v[0:3], v[104:107], v[64:79]
	s_mov_b32 s59, s49
	s_mov_b32 s1, s60
	s_mov_b32 s60, s49
	s_mov_b32 s61, s49
	s_mov_b32 s62, s49
	s_mov_b32 s63, s49
	v_mov_b64_e32 v[0:1], s[48:49]
	s_waitcnt lgkmcnt(0)
	v_mfma_f32_32x32x16_bf16 v[64:79], v[16:19], v[108:111], v[64:79]
	s_mov_b32 s84, 1
	v_mov_b32_e32 v183, v177
	v_mov_b32_e32 v185, v177
	v_mov_b64_e32 v[2:3], s[50:51]
	v_mov_b64_e32 v[4:5], s[52:53]
	v_mov_b64_e32 v[6:7], s[54:55]
	v_mov_b64_e32 v[8:9], s[56:57]
	v_mov_b64_e32 v[10:11], s[58:59]
	v_mov_b64_e32 v[12:13], s[60:61]
	v_mov_b64_e32 v[14:15], s[62:63]
	s_mov_b32 s62, 0xfffdc000
	s_movk_i32 s61, 0x180
	s_mov_b32 s60, s1
	s_mov_b32 s59, s0
	ds_read_b128 v[16:19], v25 offset:128
	ds_read_b128 v[20:23], v26 offset:128
	s_waitcnt lgkmcnt(1)
	v_mfma_f32_32x32x16_bf16 v[64:79], v[16:19], v[112:115], v[64:79]
	s_waitcnt lgkmcnt(0)
	v_mfma_f32_32x32x16_bf16 v[64:79], v[20:23], v[116:119], v[64:79]
	ds_read_b128 v[16:19], v27 offset:128
	ds_read_b128 v[20:23], v28 offset:128
	s_waitcnt lgkmcnt(1)
	v_mfma_f32_32x32x16_bf16 v[64:79], v[16:19], v[120:123], v[64:79]
	s_waitcnt lgkmcnt(0)
	v_mfma_f32_32x32x16_bf16 v[64:79], v[20:23], v[124:127], v[64:79]
	ds_read_b128 v[16:19], v25 offset:256
	ds_read_b128 v[20:23], v26 offset:256
	s_waitcnt lgkmcnt(1)
	v_mfma_f32_32x32x16_bf16 v[64:79], v[16:19], v[128:131], v[64:79]
	s_waitcnt lgkmcnt(0)
	v_mfma_f32_32x32x16_bf16 v[64:79], v[20:23], v[132:135], v[64:79]
	ds_read_b128 v[16:19], v27 offset:256
	ds_read_b128 v[20:23], v28 offset:256
	s_waitcnt lgkmcnt(1)
	v_mfma_f32_32x32x16_bf16 v[64:79], v[16:19], v[136:139], v[64:79]
	s_waitcnt lgkmcnt(0)
	v_mfma_f32_32x32x16_bf16 v[64:79], v[20:23], v[140:143], v[64:79]
	s_waitcnt lgkmcnt(0)
	s_barrier
	v_lshlrev_b32_e32 v198, 2, v24
	s_lshl_b32 s50, s40, 7
	v_readlane_b32 s0, v255, 54
	v_mov_b64_e32 v[30:31], v[14:15]
	v_mov_b64_e32 v[46:47], v[14:15]
	v_mov_b64_e32 v[62:63], v[14:15]
	v_lshl_add_u32 v203, v180, 7, 0
	s_add_i32 s51, s0, s50
	v_mov_b32_e32 v204, 0xf149f2ca
	v_mov_b32_e32 v226, 0
	v_mov_b32_e32 v227, v226
	v_mov_b32_e32 v228, v226
	v_mov_b32_e32 v229, v226
	v_mov_b32_e32 v230, v226
	v_mov_b32_e32 v231, v226
	v_mov_b32_e32 v232, v226
	v_mov_b32_e32 v233, v226
	v_mov_b32_e32 v234, v226
	v_mov_b32_e32 v235, v226
	v_mov_b32_e32 v236, v226
	v_mov_b32_e32 v237, v226
	v_mov_b32_e32 v238, v226
	v_mov_b32_e32 v239, v226
	v_mov_b32_e32 v240, v226
	v_mov_b32_e32 v241, v226
	v_mov_b32_e32 v242, 0xff7fffff
	v_mov_b32_e32 v243, 0
	v_mov_b64_e32 v[28:29], v[12:13]
	v_mov_b64_e32 v[26:27], v[10:11]
	v_mov_b64_e32 v[24:25], v[8:9]
	v_mov_b64_e32 v[22:23], v[6:7]
	v_mov_b64_e32 v[20:21], v[4:5]
	v_mov_b64_e32 v[18:19], v[2:3]
	v_mov_b64_e32 v[16:17], v[0:1]
	v_mov_b64_e32 v[44:45], v[12:13]
	v_mov_b64_e32 v[42:43], v[10:11]
	v_mov_b64_e32 v[40:41], v[8:9]
	v_mov_b64_e32 v[38:39], v[6:7]
	v_mov_b64_e32 v[36:37], v[4:5]
	v_mov_b64_e32 v[34:35], v[2:3]
	v_mov_b64_e32 v[32:33], v[0:1]
	v_mov_b64_e32 v[60:61], v[12:13]
	v_mov_b64_e32 v[58:59], v[10:11]
	v_mov_b64_e32 v[56:57], v[8:9]
	v_mov_b64_e32 v[54:55], v[6:7]
	v_mov_b64_e32 v[52:53], v[4:5]
	v_mov_b64_e32 v[50:51], v[2:3]
	v_mov_b64_e32 v[48:49], v[0:1]
	v_mov_b32_e32 v190, v177
	s_mov_b32 s0, s49
	s_mov_b32 s53, 2
	s_cmp_lt_i32 s51, 0
	s_mov_b32 s54, s0
	s_cbranch_scc1 .LBB0_477

; #define LAS __attribute__((address_space(3)))
; __device__ __forceinline__ float max_xor32(float x) { const u32x2 r = __builtin_amdgcn_permlane32_swap(__float_as_uint(x), __float_as_uint(x), false, false); return fmaxf(__uint_as_float(r.x), __uint_as_float(r.y)); }
; #define MFMA32(a, b, c) __builtin_amdgcn_mfma_f32_32x32x16_bf16((a), (b), (c), 0, 0, 0)
; #define ATT_KRD(dst, g) do { _Pragma("unroll") for (int q_ = 0; q_ < 4; ++q_) dst[q_] = *(const LAS bf16x8*)(kb + kro[q_] + (g) * 128); } while (0)
; __device__ __forceinline__ void attn_unit(LAS unsigned char* lds, const bf16_t* Qg, const bf16_t* Kg, const bf16_t* Vtg, bf16_t* Og, int bh, int qb, int tid_, int wave, int lane_) {
;     ...
;     for (int j = 0; j < nt; ++j) {
;         const int relc = 64 * (j - 2 * qb) + 32 * kh - 32 * rg;
;         const int j3 = (j + 3 < nt) ? j + 3 : nt - 1, j2 = (j + 2 < nt) ? j + 2 : nt - 1;
;         const LAS unsigned char* kb = lds + KRING + s1 * KTILE;
;         const LAS unsigned char* vb = lds + s0 * VTILE;
;         if (relc >= 0) {
;             const int thr = (relc == 0) ? r : -1;
; #pragma unroll
;             for (int i = 0; i < 16; ++i) { const int key = (i & 3) + 8 * (i >> 2) + 4 * hi; if (key > thr) sc[i] = NINF; }
;         }
;     ...
;         bf16x8 fa[4], fb[4];
;         ATT_KRD(fa, 0); ATT_KRD(fb, 1);
; #pragma unroll
;         for (int i = 0; i < 16; ++i) sn[i] = 0.f;
;         float mx = sc[0];
; #pragma unroll
;         for (int i = 1; i < 16; ++i) mx = fmaxf(mx, sc[i]);
;         mx = max_xor32(mx);
; #pragma unroll
;         for (int q = 0; q < 4; ++q) sn = MFMA32(fa[q], qf[q], sn);
;         ATT_KRD(fa, 2);
;         __builtin_amdgcn_sched_barrier(0);
;         if (__builtin_amdgcn_ballot_w64(mx > mrun + 8.f) != 0ull) {
;             const float mnew = fmaxf(mrun, mx); const float alpha = __builtin_amdgcn_exp2f(mrun - mnew); mrun = mnew; lrun *= alpha;
; #pragma unroll
;             for (int dt = 0; dt < 4; ++dt) o[dt] = o[dt] * alpha;
;         }
.LBB0_478:
	s_mul_i32 s0, s84, 0x6000
	s_add_i32 s0, s0, 0
	v_add_u32_e32 v148, s0, v191
	ds_read_b128 v[64:67], v148
	v_add_u32_e32 v156, s0, v197
	ds_read_b128 v[144:147], v156
	v_add_u32_e32 v160, s0, v199
	v_add_u32_e32 v192, s0, v200
	ds_read_b128 v[206:209], v192
	ds_read_b128 v[164:167], v148 offset:128
	ds_read_b128 v[152:155], v160
	ds_read_b128 v[168:171], v160 offset:128
	s_waitcnt lgkmcnt(0)
	v_mfma_f32_32x32x16_bf16 v[64:79], v[64:67], v[96:99], v[226:241]
	v_max_f32_e32 v149, v80, v81
	v_max3_f32 v157, v149, v82, v83
	ds_read_b128 v[148:151], v148 offset:256
	s_waitcnt lgkmcnt(5)
	v_mfma_f32_32x32x16_bf16 v[64:79], v[144:147], v[100:103], v[64:79]
	v_max3_f32 v144, v157, v84, v85
	v_max3_f32 v144, v144, v86, v87
	v_max3_f32 v144, v144, v88, v89
	v_max3_f32 v144, v144, v90, v91
	v_max3_f32 v144, v144, v92, v93
	v_max3_f32 v193, v144, v94, v95
	v_mov_b32_e32 v194, v193
	s_waitcnt lgkmcnt(2)
	v_mfma_f32_32x32x16_bf16 v[64:79], v[152:155], v[104:107], v[64:79]
	ds_read_b128 v[172:175], v156 offset:128
	ds_read_b128 v[156:159], v156 offset:256
	ds_read_b128 v[152:155], v160 offset:256
	ds_read_b128 v[160:163], v192 offset:128
	ds_read_b128 v[144:147], v192 offset:256
	v_permlane32_swap_b32_e32 v193, v194
	v_max_f32_e32 v205, v193, v194
	v_mfma_f32_32x32x16_bf16 v[64:79], v[206:209], v[108:111], v[64:79]
	v_cmp_gt_f32_e32 vcc, v205, v242
	s_cbranch_vccz .LBB0_480
	v_add_f32_e32 v192, v205, v243
	v_max_f32_e32 v193, v204, v204
	v_max_f32_e32 v193, v193, v192
	v_sub_f32_e32 v192, v204, v193
	v_sub_f32_e32 v244, v243, v193
	v_exp_f32_e32 v192, v192
	v_mov_b32_e32 v204, v193
	v_mov_b32_e32 v243, v193
	v_mov_b32_e32 v242, 0x41000000
	v_pk_mul_f32 v[62:63], v[62:63], v[192:193] op_sel_hi:[1,0]
	v_pk_mul_f32 v[60:61], v[60:61], v[192:193] op_sel_hi:[1,0]
	v_pk_mul_f32 v[58:59], v[58:59], v[192:193] op_sel_hi:[1,0]
	v_pk_mul_f32 v[56:57], v[56:57], v[192:193] op_sel_hi:[1,0]
	v_pk_mul_f32 v[54:55], v[54:55], v[192:193] op_sel_hi:[1,0]
	v_pk_mul_f32 v[52:53], v[52:53], v[192:193] op_sel_hi:[1,0]
	v_pk_mul_f32 v[50:51], v[50:51], v[192:193] op_sel_hi:[1,0]
	v_pk_mul_f32 v[48:49], v[48:49], v[192:193] op_sel_hi:[1,0]
	v_pk_mul_f32 v[46:47], v[46:47], v[192:193] op_sel_hi:[1,0]
	v_pk_mul_f32 v[44:45], v[44:45], v[192:193] op_sel_hi:[1,0]
	v_pk_mul_f32 v[42:43], v[42:43], v[192:193] op_sel_hi:[1,0]
	v_pk_mul_f32 v[40:41], v[40:41], v[192:193] op_sel_hi:[1,0]
	v_pk_mul_f32 v[38:39], v[38:39], v[192:193] op_sel_hi:[1,0]
	v_pk_mul_f32 v[36:37], v[36:37], v[192:193] op_sel_hi:[1,0]
	v_pk_mul_f32 v[34:35], v[34:35], v[192:193] op_sel_hi:[1,0]
	v_pk_mul_f32 v[32:33], v[32:33], v[192:193] op_sel_hi:[1,0]
	v_pk_mul_f32 v[30:31], v[30:31], v[192:193] op_sel_hi:[1,0]
	v_pk_mul_f32 v[28:29], v[28:29], v[192:193] op_sel_hi:[1,0]
	v_pk_mul_f32 v[26:27], v[26:27], v[192:193] op_sel_hi:[1,0]
	v_pk_mul_f32 v[24:25], v[24:25], v[192:193] op_sel_hi:[1,0]
	v_pk_mul_f32 v[22:23], v[22:23], v[192:193] op_sel_hi:[1,0]
	v_pk_mul_f32 v[20:21], v[20:21], v[192:193] op_sel_hi:[1,0]
	v_pk_mul_f32 v[18:19], v[18:19], v[192:193] op_sel_hi:[1,0]
	v_pk_mul_f32 v[16:17], v[16:17], v[192:193] op_sel_hi:[1,0]
	v_pk_mul_f32 v[14:15], v[14:15], v[192:193] op_sel_hi:[1,0]
	v_pk_mul_f32 v[12:13], v[12:13], v[192:193] op_sel_hi:[1,0]
	v_pk_mul_f32 v[10:11], v[10:11], v[192:193] op_sel_hi:[1,0]
	v_pk_mul_f32 v[8:9], v[8:9], v[192:193] op_sel_hi:[1,0]
	v_pk_mul_f32 v[6:7], v[6:7], v[192:193] op_sel_hi:[1,0]
	v_pk_mul_f32 v[4:5], v[4:5], v[192:193] op_sel_hi:[1,0]
	v_pk_mul_f32 v[2:3], v[2:3], v[192:193] op_sel_hi:[1,0]
	v_pk_mul_f32 v[0:1], v[0:1], v[192:193] op_sel_hi:[1,0]
	v_mul_f32_e32 v190, v190, v192
	v_add_f32_e32 v80, v80, v244
	v_add_f32_e32 v81, v81, v244
	v_add_f32_e32 v82, v82, v244
	v_add_f32_e32 v83, v83, v244
	v_add_f32_e32 v84, v84, v244
	v_add_f32_e32 v85, v85, v244
	v_add_f32_e32 v86, v86, v244
	v_add_f32_e32 v87, v87, v244
	v_add_f32_e32 v88, v88, v244
	v_add_f32_e32 v89, v89, v244
	v_add_f32_e32 v90, v90, v244
	v_add_f32_e32 v91, v91, v244
	v_add_f32_e32 v92, v92, v244
	v_add_f32_e32 v93, v93, v244
	v_add_f32_e32 v94, v94, v244
	v_add_f32_e32 v95, v95, v244
	v_add_f32_e32 v64, v64, v244
	v_add_f32_e32 v65, v65, v244
	v_add_f32_e32 v66, v66, v244
	v_add_f32_e32 v67, v67, v244
	v_add_f32_e32 v68, v68, v244
	v_add_f32_e32 v69, v69, v244
	v_add_f32_e32 v70, v70, v244
	v_add_f32_e32 v71, v71, v244
	v_add_f32_e32 v72, v72, v244
	v_add_f32_e32 v73, v73, v244
	v_add_f32_e32 v74, v74, v244
	v_add_f32_e32 v75, v75, v244
	v_add_f32_e32 v76, v76, v244
	v_add_f32_e32 v77, v77, v244
	v_add_f32_e32 v78, v78, v244
	v_add_f32_e32 v79, v79, v244
	v_sub_f32_e32 v226, 0, v193
	v_mov_b32_e32 v227, v226
	v_mov_b32_e32 v228, v226
	v_mov_b32_e32 v229, v226
	v_mov_b32_e32 v230, v226
	v_mov_b32_e32 v231, v226
	v_mov_b32_e32 v232, v226
	v_mov_b32_e32 v233, v226
	v_mov_b32_e32 v234, v226
	v_mov_b32_e32 v235, v226
	v_mov_b32_e32 v236, v226
	v_mov_b32_e32 v237, v226
	v_mov_b32_e32 v238, v226
	v_mov_b32_e32 v239, v226
	v_mov_b32_e32 v240, v226
	v_mov_b32_e32 v241, v226
; __device__ __forceinline__ unsigned pk2(float a, float b) { f32x2_t v = {a, b}; bf16x2v_t r = __builtin_convertvector(v, bf16x2v_t); return __builtin_bit_cast(unsigned, r); }
; __device__ __forceinline__ void attn_unit(LAS unsigned char* lds, const bf16_t* Qg, const bf16_t* Kg, const bf16_t* Vtg, bf16_t* Og, int bh, int qb, int tid_, int wave, int lane_) {
;     ...
;         float ps = 0.f; u32x4 p0, p1;
; #pragma unroll
;         for (int q = 0; q < 4; ++q) sn = MFMA32(fb[q], qf[4 + q], sn);
; #pragma unroll
;         for (int i = 0; i < 8; ++i) { sc[i] = __builtin_amdgcn_exp2f(sc[i] - mrun); ps += sc[i]; }
;         p0.x = pk2(sc[0], sc[1]); p0.y = pk2(sc[2], sc[3]); p0.z = pk2(sc[4], sc[5]); p0.w = pk2(sc[6], sc[7]);
;         __builtin_amdgcn_sched_barrier(0);
; #pragma unroll
;         for (int dt = 0; dt < 4; ++dt) fb[dt] = *(const LAS bf16x8*)(vb + vro[0] + dt * 4096);
;         __builtin_amdgcn_sched_barrier(0);
;         ATT_ISSUE_K(j3, s0);
;         __builtin_amdgcn_sched_barrier(0);
; #pragma unroll
;         for (int q = 0; q < 4; ++q) sn = MFMA32(fa[q], qf[8 + q], sn);
; #pragma unroll
;         for (int i = 8; i < 12; ++i) { sc[i] = __builtin_amdgcn_exp2f(sc[i] - mrun); ps += sc[i]; }
;         p1.x = pk2(sc[8], sc[9]); p1.y = pk2(sc[10], sc[11]);
;         __builtin_amdgcn_sched_barrier(0);
;         ATT_ISSUE_V(j2, s2);
;         __builtin_amdgcn_sched_barrier(0);
; #pragma unroll
;         for (int dt = 0; dt < 4; ++dt) fa[dt] = *(const LAS bf16x8*)(vb + vro[1] + dt * 4096);
;         { const bf16x8 pf0 = __builtin_bit_cast(bf16x8, p0);
;           o[0] = MFMA32(fb[0], pf0, o[0]); o[1] = MFMA32(fb[1], pf0, o[1]); o[2] = MFMA32(fb[2], pf0, o[2]); o[3] = MFMA32(fb[3], pf0, o[3]); }
; #pragma unroll
;         for (int i = 12; i < 16; ++i) { sc[i] = __builtin_amdgcn_exp2f(sc[i] - mrun); ps += sc[i]; }
;         p1.z = pk2(sc[12], sc[13]); p1.w = pk2(sc[14], sc[15]);
;         lrun += ps;
;         __builtin_amdgcn_sched_barrier(0);
;         { const bf16x8 pf1 = __builtin_bit_cast(bf16x8, p1);
;           o[0] = MFMA32(fa[0], pf1, o[0]); o[1] = MFMA32(fa[1], pf1, o[1]); o[2] = MFMA32(fa[2], pf1, o[2]); o[3] = MFMA32(fa[3], pf1, o[3]); }
;         asm volatile("s_waitcnt vmcnt(5) lgkmcnt(0)" ::: "memory"); __builtin_amdgcn_s_barrier(); asm volatile("" ::: "memory");
;         sc = sn;
;         { const int t = s0; s0 = s1; s1 = s2; s2 = t; }
;     }
.LBB0_480:
	v_mfma_f32_32x32x16_bf16 v[64:79], v[164:167], v[112:115], v[64:79]
	v_exp_f32_e32 v192, v80
	v_exp_f32_e32 v193, v81
	v_exp_f32_e32 v194, v82
	s_waitcnt lgkmcnt(0)
	v_mfma_f32_32x32x16_bf16 v[64:79], v[172:175], v[116:119], v[64:79]
	v_exp_f32_e32 v205, v83
	v_exp_f32_e32 v206, v84
	v_exp_f32_e32 v207, v85
	v_exp_f32_e32 v208, v86
	v_mfma_f32_32x32x16_bf16 v[64:79], v[168:171], v[120:123], v[64:79]
	s_add_i32 s0, s52, 3
	v_exp_f32_e32 v209, v87
	s_cmp_lt_u32 s0, s89
	s_cselect_b32 s0, s0, s45
	s_add_i32 s1, s52, 2
	s_cmp_lt_u32 s52, s44
	s_cselect_b32 s48, s1, s45
	v_cvt_pk_bf16_f32 v80, v192, v193
	v_cvt_pk_bf16_f32 v81, v194, v205
	v_cvt_pk_bf16_f32 v82, v206, v207
	v_cvt_pk_bf16_f32 v83, v208, v209
	v_lshl_add_u32 v84, s54, 14, v203
	v_add_u32_e32 v210, 0x12000, v84
	v_add_u32_e32 v172, v210, v201
	ds_read_b128 v[84:87], v172
	ds_read_b128 v[164:167], v172 offset:4096
	ds_read_b128 v[168:171], v172 offset:8192
	ds_read_b128 v[172:175], v172 offset:12288
	v_add_f32_e32 v192, v193, v192
	v_add_f32_e32 v192, v194, v192
	v_add_f32_e32 v192, v205, v192
	v_add_f32_e32 v192, v206, v192
	v_add_f32_e32 v192, v207, v192
	v_add_f32_e32 v192, v208, v192
	v_add_f32_e32 v194, v209, v192
	s_mul_hi_u32 s1, s0, 0x6000
	s_mulk_i32 s0, 0x6000
	s_add_u32 s0, s92, s0
	s_mul_i32 s4, s54, 0x6000
	s_addc_u32 s1, s93, s1
	s_add_i32 s4, s71, s4
	v_lshl_add_u64 v[192:193], s[0:1], 0, v[176:177]
	s_mov_b32 m0, s4
	s_waitcnt lgkmcnt(5)
	v_mfma_f32_32x32x16_bf16 v[64:79], v[160:163], v[124:127], v[64:79]
	global_load_lds_dwordx4 v[192:193], off
	v_lshl_add_u64 v[192:193], s[0:1], 0, v[182:183]
	s_add_i32 m0, s4, 0x400
	s_nop 0
	global_load_lds_dwordx4 v[192:193], off
	v_lshl_add_u64 v[192:193], s[0:1], 0, v[184:185]
	s_add_i32 m0, s4, 0x800
	s_nop 0
	global_load_lds_dwordx4 v[192:193], off
	v_mfma_f32_32x32x16_bf16 v[64:79], v[148:151], v[128:131], v[64:79]
	v_exp_f32_e32 v88, v88
	v_exp_f32_e32 v89, v89
	v_exp_f32_e32 v90, v90
	v_mfma_f32_32x32x16_bf16 v[64:79], v[156:159], v[132:135], v[64:79]
	v_exp_f32_e32 v91, v91
	v_add_f32_e32 v148, v88, v194
	v_add_f32_e32 v148, v89, v148
	v_add_f32_e32 v148, v90, v148
	v_add_f32_e32 v156, v91, v148
	v_cvt_pk_bf16_f32 v88, v88, v89
	v_cvt_pk_bf16_f32 v89, v90, v91
	v_mfma_f32_32x32x16_bf16 v[64:79], v[152:155], v[136:139], v[64:79]
	s_waitcnt lgkmcnt(0)
	v_mfma_f32_32x32x16_bf16 v[64:79], v[144:147], v[140:143], v[64:79]
	s_lshl_b64 s[0:1], s[48:49], 7
	s_add_u32 s0, s94, s0
	s_addc_u32 s1, s95, s1
	s_lshl_b32 s4, s53, 14
	s_add_i32 s4, s4, 0
	s_add_i32 s4, s4, s68
	s_add_i32 m0, s4, 0x12000
	v_lshl_add_u64 v[90:91], s[0:1], 0, v[186:187]
	global_load_lds_dwordx4 v[90:91], off
	v_lshl_add_u64 v[90:91], s[0:1], 0, v[188:189]
	s_add_i32 m0, s4, 0x12400
	s_nop 0
	global_load_lds_dwordx4 v[90:91], off
	v_add_u32_e32 v90, v210, v202
	v_mfma_f32_32x32x16_bf16 v[48:63], v[84:87], v[80:83], v[48:63]
	ds_read_b128 v[84:87], v90
	ds_read_b128 v[144:147], v90 offset:4096
	ds_read_b128 v[148:151], v90 offset:8192
	ds_read_b128 v[152:155], v90 offset:12288
	v_exp_f32_e32 v90, v92
	v_exp_f32_e32 v91, v93
	v_exp_f32_e32 v92, v94
	v_mfma_f32_32x32x16_bf16 v[32:47], v[164:167], v[80:83], v[32:47]
	v_exp_f32_e32 v93, v95
	v_add_f32_e32 v94, v90, v156
	v_add_f32_e32 v94, v91, v94
	v_add_f32_e32 v94, v92, v94
	v_add_f32_e32 v94, v93, v94
	v_add_f32_e32 v190, v190, v94
	v_mfma_f32_32x32x16_bf16 v[16:31], v[168:171], v[80:83], v[16:31]
	v_cvt_pk_bf16_f32 v90, v90, v91
	v_cvt_pk_bf16_f32 v91, v92, v93
	v_mfma_f32_32x32x16_bf16 v[0:15], v[172:175], v[80:83], v[0:15]
	s_waitcnt lgkmcnt(0)
	v_mfma_f32_32x32x16_bf16 v[48:63], v[84:87], v[88:91], v[48:63]
	s_waitcnt vmcnt(5) lgkmcnt(0)
	s_barrier
	s_add_i32 s52, s52, 1
	s_add_i32 s51, s51, 64
	s_cmp_eq_u32 s89, s52
	v_mfma_f32_32x32x16_bf16 v[32:47], v[144:147], v[88:91], v[32:47]
	v_mfma_f32_32x32x16_bf16 v[16:31], v[148:151], v[88:91], v[16:31]
	v_mfma_f32_32x32x16_bf16 v[0:15], v[152:155], v[88:91], v[0:15]
	s_cbranch_scc1 .LBB0_482
	s_mov_b32 s0, s84
	s_mov_b32 s84, s53
	s_mov_b32 s53, s54
	s_cmp_lt_i32 s51, 0
	s_mov_b32 s54, s0
	s_cbranch_scc0 .LBB0_476
	s_branch .LBB0_477

; #define ATT_ISSUE_K(jt, stage) do { _Pragma("unroll") for (int i_ = 0; i_ < 3; ++i_) ATT_DMA(kg + (size_t)(jt) * KTILE + kgo[i_], KRING + (stage) * KTILE + (wave * 3 + i_) * 1024); } while (0)
; __device__ __forceinline__ void attn_unit(LAS unsigned char* lds, const bf16_t* Qg, const bf16_t* Kg, const bf16_t* Vtg, bf16_t* Og, int bh, int qb, int tid_, int wave, int lane_) {
;     int tid = tid_; asm volatile("" : "+v"(tid));
;     const int lane = tid & 63;
;     const int rg = wave & 3, kh = wave >> 2, r = lane & 31, hi = lane >> 5;
;     const int b = bh >> 2, h = bh & 3;
;     const int nt = 2 * (qb + 1);
;     const float NEG = -1e30f;
;     bf16x8 qf[12];
;     { const bf16_t* qp = Qg + ((size_t)bh * SEQ + 128 * qb + 32 * rg + r) * QKD + 8 * hi;
; #pragma unroll
;       for (int kk = 0; kk < 12; ++kk) qf[kk] = *(const bf16x8*)(qp + 16 * kk); }
;     const unsigned char* kg = (const unsigned char*)(Kg + (size_t)bh * SEQ * QKD);
;     const unsigned char* vg = (const unsigned char*)(Vtg + (size_t)bh * VD * SEQ);
;     unsigned kgo[3], vgo[2];
; #pragma unroll
;     for (int i = 0; i < 3; ++i) { const int a = (wave * 3 + i) * 1024 + lane * 16, row = a / 384, cp = (a % 384) >> 4, cl = (cp & ~7) | ((cp ^ (row >> 1)) & 7); kgo[i] = (unsigned)(row * 384 + cl * 16); }
; #pragma unroll
;     for (int i = 0; i < 2; ++i) { const int a = (wave * 2 + i) * 1024 + lane * 16, row = a >> 7, cp = (a & 127) >> 4, cl = (cp ^ (row >> 1)) & 7; vgo[i] = (unsigned)(row * (SEQ * 2) + cl * 16); }
;     const int sw = (r >> 1) & 7;
;     unsigned kro[4], vro[2];
; #pragma unroll
;     for (int q = 0; q < 4; ++q) kro[q] = (unsigned)((32 * kh + r) * 384 + (((2 * q + hi) ^ sw) * 16));
; #pragma unroll
;     for (int s = 0; s < 2; ++s) vro[s] = (unsigned)(VRING + r * 128 + (((4 * kh + 2 * s + hi) ^ sw) * 16));
;     f32x16 o[4]; float mrun = NEG, lrun = 0.f;
; #pragma unroll
;     for (int dt = 0; dt < 4; ++dt)
; #pragma unroll
;         for (int i = 0; i < 16; ++i) o[dt][i] = 0.f;
;     ATT_ISSUE_K(0, 0); ATT_ISSUE_V(0, 0); ATT_ISSUE_K(1, 1);
;     ATT_ISSUE_K((2 < nt) ? 2 : nt - 1, 2); ATT_ISSUE_V(1, 1);
;     asm volatile("s_waitcnt vmcnt(5)" ::: "memory"); __builtin_amdgcn_s_barrier(); asm volatile("" ::: "memory");
.LBB0_486:
	s_lshl_b32 s52, s40, 1
	s_ashr_i32 s51, s50, 31
	v_mov_b32_e32 v6, v254
	s_add_u32 s0, s41, s50
	s_barrier
	s_addc_u32 s12, 0, s51
	v_and_b32_e32 v191, 31, v6
	s_or_b32 s0, s0, s97
	v_or_b32_e32 v2, s0, v191
	v_readlane_b32 s0, v255, 36
	v_readlane_b32 s1, v255, 37
	v_bfe_u32 v190, v6, 5, 1
	v_lshlrev_b32_e32 v176, 4, v190
	v_mov_b64_e32 v[0:1], s[0:1]
	v_mad_u64_u32 v[0:1], s[0:1], v2, s61, v[0:1]
	v_mad_i32_i24 v1, s12, v195, v1
	v_and_b32_e32 v181, 63, v6
	v_lshl_add_u64 v[0:1], v[0:1], 0, v[176:177]
	global_load_dwordx4 v[96:99], v[0:1], off
	global_load_dwordx4 v[100:103], v[0:1], off offset:32
	global_load_dwordx4 v[104:107], v[0:1], off offset:64
	global_load_dwordx4 v[108:111], v[0:1], off offset:96
	global_load_dwordx4 v[112:115], v[0:1], off offset:128
	global_load_dwordx4 v[116:119], v[0:1], off offset:160
	global_load_dwordx4 v[120:123], v[0:1], off offset:192
	global_load_dwordx4 v[124:127], v[0:1], off offset:224
	global_load_dwordx4 v[128:131], v[0:1], off offset:256
	global_load_dwordx4 v[132:135], v[0:1], off offset:288
	global_load_dwordx4 v[136:139], v[0:1], off offset:320
	global_load_dwordx4 v[140:143], v[0:1], off offset:352
	v_lshlrev_b32_e32 v0, 4, v181
	v_or_b32_e32 v1, s59, v0
	v_mul_hi_i32 v2, v1, s42
	v_lshrrev_b32_e32 v3, 31, v2
	v_ashrrev_i32_e32 v2, 6, v2
	v_add_u32_e32 v2, v2, v3
	v_mul_i32_i24_e32 v3, 0x180, v2
	v_lshlrev_b32_e32 v2, 3, v2
	v_sub_u32_e32 v1, v1, v3
	v_and_b32_e32 v2, 0x70, v2
	v_xad_u32 v182, v2, v1, v3
	v_or_b32_e32 v1, s60, v0
	v_mul_hi_i32 v2, v1, s42
	v_lshrrev_b32_e32 v3, 31, v2
	v_ashrrev_i32_e32 v2, 6, v2
	v_add_u32_e32 v2, v2, v3
	v_mul_i32_i24_e32 v3, 0x180, v2
	v_lshlrev_b32_e32 v2, 3, v2
	v_sub_u32_e32 v1, v1, v3
	v_and_b32_e32 v2, 0x70, v2
	v_xad_u32 v184, v2, v1, v3
	v_or_b32_e32 v1, s67, v0
	v_mul_hi_i32 v2, v1, s42
	v_lshrrev_b32_e32 v3, 31, v2
	v_ashrrev_i32_e32 v2, 6, v2
	v_add_u32_e32 v2, v2, v3
	v_mul_i32_i24_e32 v3, 0x180, v2
	v_lshlrev_b32_e32 v2, 3, v2
	v_sub_u32_e32 v1, v1, v3
	v_and_b32_e32 v2, 0x70, v2
	v_xad_u32 v186, v2, v1, v3
	v_or_b32_e32 v0, s68, v0
	v_lshlrev_b32_e32 v2, 4, v6
	v_and_b32_e32 v3, 48, v6
	s_mov_b32 m0, s71
	v_lshlrev_b32_e32 v1, 7, v0
	v_bitop3_b32 v2, v2, v3, s86 bitop3:0x6c
	v_or_b32_e32 v0, 0x400, v0
	v_and_or_b32 v176, v1, s62, v2
	v_lshrrev_b32_e32 v1, 8, v0
	global_load_lds_dwordx4 v182, s[92:93]
	s_mov_b32 m0, s91
	v_xor_b32_e32 v1, v1, v6
	v_lshlrev_b32_e32 v0, 7, v0
	global_load_lds_dwordx4 v184, s[92:93]
	s_mov_b32 m0, s74
	v_and_b32_e32 v0, 0xffffc000, v0
	v_lshlrev_b32_e32 v1, 4, v1
	global_load_lds_dwordx4 v186, s[92:93]
	s_mov_b32 m0, s96
	s_or_b32 s44, s52, 1
	v_and_or_b32 v188, v1, s86, v0
	global_load_lds_dwordx4 v176, s[94:95]
	s_mov_b32 m0, s43
	s_cmp_lt_i32 s40, 1
	global_load_lds_dwordx4 v188, s[94:95]
	s_mov_b32 m0, s75
	s_cselect_b32 s0, s44, 2
	global_load_lds_dwordx4 v182, s[38:39]
	s_mov_b32 m0, s90
	s_mul_hi_i32 s1, s0, 0x6000
	s_mulk_i32 s0, 0x6000
	global_load_lds_dwordx4 v184, s[38:39]
	s_mov_b32 m0, s2
	s_add_u32 s0, s92, s0
	global_load_lds_dwordx4 v186, s[38:39]
	s_addc_u32 s1, s93, s1
	s_mov_b32 m0, s85
	v_lshl_add_u64 v[0:1], s[94:95], 0, v[176:177]
	global_load_lds_dwordx4 v182, s[0:1]
	s_mov_b32 m0, s87
	v_mov_b32_e32 v189, v177
	global_load_lds_dwordx4 v184, s[0:1]
	s_mov_b32 m0, s3
	v_lshl_add_u64 v[2:3], s[94:95], 0, v[188:189]
	global_load_lds_dwordx4 v186, s[0:1]
	v_lshl_add_u64 v[0:1], v[0:1], 0, s[78:79]
	s_mov_b32 m0, s33
	s_nop 0
	global_load_lds_dwordx4 v[0:1], off
	v_lshl_add_u64 v[0:1], v[2:3], 0, s[78:79]
	s_mov_b32 m0, s10
	s_nop 0
	global_load_lds_dwordx4 v[0:1], off
	v_lshrrev_b32_e32 v0, 1, v6
	v_or_b32_e32 v1, s69, v191
	v_mul_lo_u32 v1, v1, s61
	v_bitop3_b32 v0, v190, v0, 7 bitop3:0x78
	v_lshl_or_b32 v199, v0, 4, v1
	s_waitcnt vmcnt(5)
	s_barrier
; #define LAS __attribute__((address_space(3)))
; #define MFMA32(a, b, c) __builtin_amdgcn_mfma_f32_32x32x16_bf16((a), (b), (c), 0, 0, 0)
; #define ATT_ISSUE_K(jt, stage) do { _Pragma("unroll") for (int i_ = 0; i_ < 3; ++i_) ATT_DMA(kg + (size_t)(jt) * KTILE + kgo[i_], KRING + (stage) * KTILE + (wave * 3 + i_) * 1024); } while (0)
; #define ATT_ISSUE_V(jt, stage) do { _Pragma("unroll") for (int i_ = 0; i_ < 2; ++i_) ATT_DMA(vg + (size_t)(jt) * 128 + vgo[i_], VRING + (stage) * VTILE + (wave * 2 + i_) * 1024); } while (0)
; __device__ __forceinline__ void attn_unit(LAS unsigned char* lds, const bf16_t* Qg, const bf16_t* Kg, const bf16_t* Vtg, bf16_t* Og, int bh, int qb, int tid_, int wave, int lane_) {
;     ...
;     f32x16 o[4]; float mrun = NEG, lrun = 0.f;
; #pragma unroll
;     for (int dt = 0; dt < 4; ++dt)
; #pragma unroll
;         for (int i = 0; i < 16; ++i) o[dt][i] = 0.f;
;     ATT_ISSUE_K(0, 0); ATT_ISSUE_V(0, 0); ATT_ISSUE_K(1, 1);
;     ATT_ISSUE_K((2 < nt) ? 2 : nt - 1, 2); ATT_ISSUE_V(1, 1);
;     asm volatile("s_waitcnt vmcnt(5)" ::: "memory"); __builtin_amdgcn_s_barrier(); asm volatile("" ::: "memory");
;     f32x16 sc, sn;
;     {
; #pragma unroll
;       for (int i = 0; i < 16; ++i) sc[i] = 0.f;
; #pragma unroll
;       for (int kk = 0; kk < 12; ++kk) { const bf16x8 kf = *(const LAS bf16x8*)(lds + KRING + kro[kk & 3] + (kk >> 2) * 128); sc = MFMA32(kf, qf[kk], sc); if ((kk & 3) == 3) __builtin_amdgcn_sched_barrier(0); } }
;     asm volatile("s_waitcnt lgkmcnt(0)" ::: "memory"); __builtin_amdgcn_s_barrier(); asm volatile("" ::: "memory");
;     const float NINF = -__builtin_inff();
;     int s0 = 0, s1 = 1, s2 = 2;
	v_add_u32_e32 v10, 0, v199
	ds_read_b128 v[2:5], v10
	v_bfe_u32 v0, v6, 1, 3
	v_bitop3_b32 v6, v190, v0, 2 bitop3:0x36
	v_lshl_or_b32 v200, v6, 4, v1
	v_add_u32_e32 v11, 0, v200
	ds_read_b128 v[6:9], v11
	s_waitcnt vmcnt(0) lgkmcnt(0)
	v_mfma_f32_32x32x16_bf16 v[64:79], v[2:5], v[96:99], 0
	v_bitop3_b32 v2, v190, v0, 4 bitop3:0x36
	v_lshl_or_b32 v201, v2, 4, v1
	v_add_u32_e32 v12, 0, v201
	ds_read_b128 v[2:5], v12
	v_mfma_f32_32x32x16_bf16 v[64:79], v[6:9], v[100:103], v[64:79]
	v_bitop3_b32 v6, v190, v0, 6 bitop3:0x36
	v_lshl_or_b32 v202, v6, 4, v1
	v_add_u32_e32 v1, 0, v202
	ds_read_b128 v[6:9], v1
	s_waitcnt lgkmcnt(1)
	v_mfma_f32_32x32x16_bf16 v[64:79], v[2:5], v[104:107], v[64:79]
	s_waitcnt lgkmcnt(0)
	v_mfma_f32_32x32x16_bf16 v[64:79], v[6:9], v[108:111], v[64:79]
	ds_read_b128 v[2:5], v10 offset:128
	ds_read_b128 v[6:9], v11 offset:128
	s_waitcnt lgkmcnt(1)
	v_mfma_f32_32x32x16_bf16 v[64:79], v[2:5], v[112:115], v[64:79]
	s_waitcnt lgkmcnt(0)
	v_mfma_f32_32x32x16_bf16 v[64:79], v[6:9], v[116:119], v[64:79]
	ds_read_b128 v[2:5], v12 offset:128
	ds_read_b128 v[6:9], v1 offset:128
	s_waitcnt lgkmcnt(1)
	v_mfma_f32_32x32x16_bf16 v[64:79], v[2:5], v[120:123], v[64:79]
	s_waitcnt lgkmcnt(0)
	v_mfma_f32_32x32x16_bf16 v[64:79], v[6:9], v[124:127], v[64:79]
	ds_read_b128 v[2:5], v10 offset:256
	ds_read_b128 v[6:9], v11 offset:256
	s_waitcnt lgkmcnt(1)
	v_mfma_f32_32x32x16_bf16 v[64:79], v[2:5], v[128:131], v[64:79]
	s_waitcnt lgkmcnt(0)
	v_mfma_f32_32x32x16_bf16 v[64:79], v[6:9], v[132:135], v[64:79]
	ds_read_b128 v[2:5], v12 offset:256
	ds_read_b128 v[6:9], v1 offset:256
	s_waitcnt lgkmcnt(1)
	v_mfma_f32_32x32x16_bf16 v[64:79], v[2:5], v[136:139], v[64:79]
	s_waitcnt lgkmcnt(0)
	v_mfma_f32_32x32x16_bf16 v[64:79], v[6:9], v[140:143], v[64:79]
	s_waitcnt lgkmcnt(0)
	s_barrier
	s_cmp_lt_i32 s40, 0
	s_cbranch_scc1 .LBB0_494
	v_or_b32_e32 v1, s70, v190
	v_bitop3_b32 v2, v190, v0, s70 bitop3:0x36
	v_bitop3_b32 v0, v1, v0, 2 bitop3:0x36
	v_mov_b32_e32 v14, v177
	v_mov_b32_e32 v15, v177
	v_lshlrev_b32_e32 v203, 4, v2
	v_lshlrev_b32_e32 v204, 4, v0
	v_mov_b32_e32 v0, v177
	v_mov_b32_e32 v1, v177
	v_mov_b32_e32 v2, v177
	v_mov_b32_e32 v3, v177
	v_mov_b32_e32 v4, v177
	v_mov_b32_e32 v5, v177
	v_mov_b32_e32 v6, v177
	v_mov_b32_e32 v7, v177
	v_mov_b32_e32 v8, v177
	v_mov_b32_e32 v9, v177
	v_mov_b32_e32 v10, v177
	v_mov_b32_e32 v11, v177
	v_mov_b32_e32 v12, v177
	v_mov_b32_e32 v13, v177
	v_mov_b64_e32 v[30:31], v[14:15]
	v_mov_b64_e32 v[46:47], v[14:15]
	v_mov_b64_e32 v[62:63], v[14:15]
	v_mov_b32_e32 v183, v177
	v_mov_b32_e32 v185, v177
	v_mov_b32_e32 v187, v177
	s_mov_b32 s53, 2
	s_add_i32 s45, s52, 2
	v_lshlrev_b32_e32 v205, 2, v190
	v_lshl_add_u32 v206, v191, 7, 0
	s_sub_i32 s54, s69, s50
	s_mov_b32 s0, 0
	s_mov_b32 s55, 1
	v_mov_b32_e32 v198, 0xf149f2ca
	v_mov_b32_e32 v226, 0
	v_mov_b32_e32 v227, v226
	v_mov_b32_e32 v228, v226
	v_mov_b32_e32 v229, v226
	v_mov_b32_e32 v230, v226
	v_mov_b32_e32 v231, v226
	v_mov_b32_e32 v232, v226
	v_mov_b32_e32 v233, v226
	v_mov_b32_e32 v234, v226
	v_mov_b32_e32 v235, v226
	v_mov_b32_e32 v236, v226
	v_mov_b32_e32 v237, v226
	v_mov_b32_e32 v238, v226
	v_mov_b32_e32 v239, v226
	v_mov_b32_e32 v240, v226
	v_mov_b32_e32 v241, v226
	v_mov_b32_e32 v242, 0xff7fffff
	v_mov_b32_e32 v243, 0
	v_mov_b32_e32 v180, 0
	v_readlane_b32 s56, v255, 55
	v_mov_b64_e32 v[28:29], v[12:13]
	v_mov_b64_e32 v[26:27], v[10:11]
	v_mov_b64_e32 v[24:25], v[8:9]
	v_mov_b64_e32 v[22:23], v[6:7]
	v_mov_b64_e32 v[20:21], v[4:5]
	v_mov_b64_e32 v[18:19], v[2:3]
	v_mov_b64_e32 v[16:17], v[0:1]
	v_mov_b64_e32 v[44:45], v[12:13]
	v_mov_b64_e32 v[42:43], v[10:11]
	v_mov_b64_e32 v[40:41], v[8:9]
	v_mov_b64_e32 v[38:39], v[6:7]
	v_mov_b64_e32 v[36:37], v[4:5]
	v_mov_b64_e32 v[34:35], v[2:3]
	v_mov_b64_e32 v[32:33], v[0:1]
	v_mov_b64_e32 v[60:61], v[12:13]
	v_mov_b64_e32 v[58:59], v[10:11]
	v_mov_b64_e32 v[56:57], v[8:9]
	v_mov_b64_e32 v[54:55], v[6:7]
	v_mov_b64_e32 v[52:53], v[4:5]
	v_mov_b64_e32 v[50:51], v[2:3]
	v_mov_b64_e32 v[48:49], v[0:1]
	s_mov_b32 s57, 0
	s_mov_b64 s[88:89], s[8:9]
	s_add_i32 s1, s54, s56
	s_cmp_lt_i32 s1, 0
	s_mov_b32 s58, s0
	s_cbranch_scc1 .LBB0_489

; #define LAS __attribute__((address_space(3)))
; __device__ __forceinline__ float max_xor32(float x) { const u32x2 r = __builtin_amdgcn_permlane32_swap(__float_as_uint(x), __float_as_uint(x), false, false); return fmaxf(__uint_as_float(r.x), __uint_as_float(r.y)); }
; #define MFMA32(a, b, c) __builtin_amdgcn_mfma_f32_32x32x16_bf16((a), (b), (c), 0, 0, 0)
; #define ATT_KRD(dst, g) do { _Pragma("unroll") for (int q_ = 0; q_ < 4; ++q_) dst[q_] = *(const LAS bf16x8*)(kb + kro[q_] + (g) * 128); } while (0)
; __device__ __forceinline__ void attn_unit(LAS unsigned char* lds, const bf16_t* Qg, const bf16_t* Kg, const bf16_t* Vtg, bf16_t* Og, int bh, int qb, int tid_, int wave, int lane_) {
;     ...
;     for (int j = 0; j < nt; ++j) {
;         const int relc = 64 * (j - 2 * qb) + 32 * kh - 32 * rg;
;         const int j3 = (j + 3 < nt) ? j + 3 : nt - 1, j2 = (j + 2 < nt) ? j + 2 : nt - 1;
;         const LAS unsigned char* kb = lds + KRING + s1 * KTILE;
;         const LAS unsigned char* vb = lds + s0 * VTILE;
;         if (relc >= 0) {
;             const int thr = (relc == 0) ? r : -1;
; #pragma unroll
;             for (int i = 0; i < 16; ++i) { const int key = (i & 3) + 8 * (i >> 2) + 4 * hi; if (key > thr) sc[i] = NINF; }
;         }
;     ...
;         bf16x8 fa[4], fb[4];
;         ATT_KRD(fa, 0); ATT_KRD(fb, 1);
; #pragma unroll
;         for (int i = 0; i < 16; ++i) sn[i] = 0.f;
;         float mx = sc[0];
; #pragma unroll
;         for (int i = 1; i < 16; ++i) mx = fmaxf(mx, sc[i]);
;         mx = max_xor32(mx);
; #pragma unroll
;         for (int q = 0; q < 4; ++q) sn = MFMA32(fa[q], qf[q], sn);
;         ATT_KRD(fa, 2);
;         __builtin_amdgcn_sched_barrier(0);
;         if (__builtin_amdgcn_ballot_w64(mx > mrun + 8.f) != 0ull) {
;             const float mnew = fmaxf(mrun, mx); const float alpha = __builtin_amdgcn_exp2f(mrun - mnew); mrun = mnew; lrun *= alpha;
; #pragma unroll
;             for (int dt = 0; dt < 4; ++dt) o[dt] = o[dt] * alpha;
;         }
.LBB0_490:
	s_mul_i32 s0, s55, 0x6000
	s_add_i32 s0, s0, 0
	v_add_u32_e32 v148, s0, v199
	ds_read_b128 v[64:67], v148
	v_add_u32_e32 v156, s0, v200
	ds_read_b128 v[144:147], v156
	v_add_u32_e32 v160, s0, v201
	v_add_u32_e32 v192, s0, v202
	ds_read_b128 v[208:211], v192
	ds_read_b128 v[164:167], v148 offset:128
	ds_read_b128 v[152:155], v160
	ds_read_b128 v[168:171], v160 offset:128
	s_waitcnt lgkmcnt(0)
	v_mfma_f32_32x32x16_bf16 v[64:79], v[64:67], v[96:99], v[226:241]
	v_max_f32_e32 v149, v80, v81
	v_max3_f32 v157, v149, v82, v83
	ds_read_b128 v[148:151], v148 offset:256
	s_waitcnt lgkmcnt(5)
	v_mfma_f32_32x32x16_bf16 v[64:79], v[144:147], v[100:103], v[64:79]
	v_max3_f32 v144, v157, v84, v85
	v_max3_f32 v144, v144, v86, v87
	v_max3_f32 v144, v144, v88, v89
	v_max3_f32 v144, v144, v90, v91
	v_max3_f32 v144, v144, v92, v93
	v_max3_f32 v193, v144, v94, v95
	v_mov_b32_e32 v194, v193
	s_waitcnt lgkmcnt(2)
	v_mfma_f32_32x32x16_bf16 v[64:79], v[152:155], v[104:107], v[64:79]
	ds_read_b128 v[172:175], v156 offset:128
	ds_read_b128 v[156:159], v156 offset:256
	ds_read_b128 v[152:155], v160 offset:256
	ds_read_b128 v[160:163], v192 offset:128
	ds_read_b128 v[144:147], v192 offset:256
	v_permlane32_swap_b32_e32 v193, v194
	v_max_f32_e32 v207, v193, v194
	v_mfma_f32_32x32x16_bf16 v[64:79], v[208:211], v[108:111], v[64:79]
	v_cmp_gt_f32_e32 vcc, v207, v242
	s_cbranch_vccz .LBB0_492
	v_add_f32_e32 v192, v207, v243
	v_max_f32_e32 v193, v198, v198
	v_max_f32_e32 v193, v193, v192
	v_sub_f32_e32 v192, v198, v193
	v_sub_f32_e32 v244, v243, v193
	v_exp_f32_e32 v192, v192
	v_mov_b32_e32 v198, v193
	v_mov_b32_e32 v243, v193
	v_mov_b32_e32 v242, 0x41000000
	v_pk_mul_f32 v[62:63], v[62:63], v[192:193] op_sel_hi:[1,0]
	v_pk_mul_f32 v[60:61], v[60:61], v[192:193] op_sel_hi:[1,0]
	v_pk_mul_f32 v[58:59], v[58:59], v[192:193] op_sel_hi:[1,0]
	v_pk_mul_f32 v[56:57], v[56:57], v[192:193] op_sel_hi:[1,0]
	v_pk_mul_f32 v[54:55], v[54:55], v[192:193] op_sel_hi:[1,0]
	v_pk_mul_f32 v[52:53], v[52:53], v[192:193] op_sel_hi:[1,0]
	v_pk_mul_f32 v[50:51], v[50:51], v[192:193] op_sel_hi:[1,0]
	v_pk_mul_f32 v[48:49], v[48:49], v[192:193] op_sel_hi:[1,0]
	v_pk_mul_f32 v[46:47], v[46:47], v[192:193] op_sel_hi:[1,0]
	v_pk_mul_f32 v[44:45], v[44:45], v[192:193] op_sel_hi:[1,0]
	v_pk_mul_f32 v[42:43], v[42:43], v[192:193] op_sel_hi:[1,0]
	v_pk_mul_f32 v[40:41], v[40:41], v[192:193] op_sel_hi:[1,0]
	v_pk_mul_f32 v[38:39], v[38:39], v[192:193] op_sel_hi:[1,0]
	v_pk_mul_f32 v[36:37], v[36:37], v[192:193] op_sel_hi:[1,0]
	v_pk_mul_f32 v[34:35], v[34:35], v[192:193] op_sel_hi:[1,0]
	v_pk_mul_f32 v[32:33], v[32:33], v[192:193] op_sel_hi:[1,0]
	v_pk_mul_f32 v[30:31], v[30:31], v[192:193] op_sel_hi:[1,0]
	v_pk_mul_f32 v[28:29], v[28:29], v[192:193] op_sel_hi:[1,0]
	v_pk_mul_f32 v[26:27], v[26:27], v[192:193] op_sel_hi:[1,0]
	v_pk_mul_f32 v[24:25], v[24:25], v[192:193] op_sel_hi:[1,0]
	v_pk_mul_f32 v[22:23], v[22:23], v[192:193] op_sel_hi:[1,0]
	v_pk_mul_f32 v[20:21], v[20:21], v[192:193] op_sel_hi:[1,0]
	v_pk_mul_f32 v[18:19], v[18:19], v[192:193] op_sel_hi:[1,0]
	v_pk_mul_f32 v[16:17], v[16:17], v[192:193] op_sel_hi:[1,0]
	v_pk_mul_f32 v[14:15], v[14:15], v[192:193] op_sel_hi:[1,0]
	v_pk_mul_f32 v[12:13], v[12:13], v[192:193] op_sel_hi:[1,0]
	v_pk_mul_f32 v[10:11], v[10:11], v[192:193] op_sel_hi:[1,0]
	v_pk_mul_f32 v[8:9], v[8:9], v[192:193] op_sel_hi:[1,0]
	v_pk_mul_f32 v[6:7], v[6:7], v[192:193] op_sel_hi:[1,0]
	v_pk_mul_f32 v[4:5], v[4:5], v[192:193] op_sel_hi:[1,0]
	v_pk_mul_f32 v[2:3], v[2:3], v[192:193] op_sel_hi:[1,0]
	v_pk_mul_f32 v[0:1], v[0:1], v[192:193] op_sel_hi:[1,0]
	v_mul_f32_e32 v180, v180, v192
	v_add_f32_e32 v80, v80, v244
	v_add_f32_e32 v81, v81, v244
	v_add_f32_e32 v82, v82, v244
	v_add_f32_e32 v83, v83, v244
	v_add_f32_e32 v84, v84, v244
	v_add_f32_e32 v85, v85, v244
	v_add_f32_e32 v86, v86, v244
	v_add_f32_e32 v87, v87, v244
	v_add_f32_e32 v88, v88, v244
	v_add_f32_e32 v89, v89, v244
	v_add_f32_e32 v90, v90, v244
	v_add_f32_e32 v91, v91, v244
	v_add_f32_e32 v92, v92, v244
	v_add_f32_e32 v93, v93, v244
	v_add_f32_e32 v94, v94, v244
	v_add_f32_e32 v95, v95, v244
	v_add_f32_e32 v64, v64, v244
	v_add_f32_e32 v65, v65, v244
	v_add_f32_e32 v66, v66, v244
	v_add_f32_e32 v67, v67, v244
	v_add_f32_e32 v68, v68, v244
	v_add_f32_e32 v69, v69, v244
	v_add_f32_e32 v70, v70, v244
	v_add_f32_e32 v71, v71, v244
	v_add_f32_e32 v72, v72, v244
	v_add_f32_e32 v73, v73, v244
	v_add_f32_e32 v74, v74, v244
	v_add_f32_e32 v75, v75, v244
	v_add_f32_e32 v76, v76, v244
	v_add_f32_e32 v77, v77, v244
	v_add_f32_e32 v78, v78, v244
	v_add_f32_e32 v79, v79, v244
	v_sub_f32_e32 v226, 0, v193
	v_mov_b32_e32 v227, v226
	v_mov_b32_e32 v228, v226
	v_mov_b32_e32 v229, v226
	v_mov_b32_e32 v230, v226
	v_mov_b32_e32 v231, v226
	v_mov_b32_e32 v232, v226
	v_mov_b32_e32 v233, v226
	v_mov_b32_e32 v234, v226
	v_mov_b32_e32 v235, v226
	v_mov_b32_e32 v236, v226
	v_mov_b32_e32 v237, v226
	v_mov_b32_e32 v238, v226
	v_mov_b32_e32 v239, v226
	v_mov_b32_e32 v240, v226
	v_mov_b32_e32 v241, v226
; __device__ __forceinline__ unsigned pk2(float a, float b) { f32x2_t v = {a, b}; bf16x2v_t r = __builtin_convertvector(v, bf16x2v_t); return __builtin_bit_cast(unsigned, r); }
; __device__ __forceinline__ void attn_unit(LAS unsigned char* lds, const bf16_t* Qg, const bf16_t* Kg, const bf16_t* Vtg, bf16_t* Og, int bh, int qb, int tid_, int wave, int lane_) {
;     ...
;         float ps = 0.f; u32x4 p0, p1;
; #pragma unroll
;         for (int q = 0; q < 4; ++q) sn = MFMA32(fb[q], qf[4 + q], sn);
; #pragma unroll
;         for (int i = 0; i < 8; ++i) { sc[i] = __builtin_amdgcn_exp2f(sc[i] - mrun); ps += sc[i]; }
;         p0.x = pk2(sc[0], sc[1]); p0.y = pk2(sc[2], sc[3]); p0.z = pk2(sc[4], sc[5]); p0.w = pk2(sc[6], sc[7]);
;         __builtin_amdgcn_sched_barrier(0);
; #pragma unroll
;         for (int dt = 0; dt < 4; ++dt) fb[dt] = *(const LAS bf16x8*)(vb + vro[0] + dt * 4096);
;         __builtin_amdgcn_sched_barrier(0);
;         ATT_ISSUE_K(j3, s0);
;         __builtin_amdgcn_sched_barrier(0);
; #pragma unroll
;         for (int q = 0; q < 4; ++q) sn = MFMA32(fa[q], qf[8 + q], sn);
; #pragma unroll
;         for (int i = 8; i < 12; ++i) { sc[i] = __builtin_amdgcn_exp2f(sc[i] - mrun); ps += sc[i]; }
;         p1.x = pk2(sc[8], sc[9]); p1.y = pk2(sc[10], sc[11]);
;         __builtin_amdgcn_sched_barrier(0);
;         ATT_ISSUE_V(j2, s2);
;         __builtin_amdgcn_sched_barrier(0);
; #pragma unroll
;         for (int dt = 0; dt < 4; ++dt) fa[dt] = *(const LAS bf16x8*)(vb + vro[1] + dt * 4096);
;         { const bf16x8 pf0 = __builtin_bit_cast(bf16x8, p0);
;           o[0] = MFMA32(fb[0], pf0, o[0]); o[1] = MFMA32(fb[1], pf0, o[1]); o[2] = MFMA32(fb[2], pf0, o[2]); o[3] = MFMA32(fb[3], pf0, o[3]); }
; #pragma unroll
;         for (int i = 12; i < 16; ++i) { sc[i] = __builtin_amdgcn_exp2f(sc[i] - mrun); ps += sc[i]; }
;         p1.z = pk2(sc[12], sc[13]); p1.w = pk2(sc[14], sc[15]);
;         lrun += ps;
;         __builtin_amdgcn_sched_barrier(0);
;         { const bf16x8 pf1 = __builtin_bit_cast(bf16x8, p1);
;           o[0] = MFMA32(fa[0], pf1, o[0]); o[1] = MFMA32(fa[1], pf1, o[1]); o[2] = MFMA32(fa[2], pf1, o[2]); o[3] = MFMA32(fa[3], pf1, o[3]); }
;         asm volatile("s_waitcnt vmcnt(5) lgkmcnt(0)" ::: "memory"); __builtin_amdgcn_s_barrier(); asm volatile("" ::: "memory");
;         sc = sn;
;         { const int t = s0; s0 = s1; s1 = s2; s2 = t; }
;     }
.LBB0_492:
	v_mfma_f32_32x32x16_bf16 v[64:79], v[164:167], v[112:115], v[64:79]
	v_exp_f32_e32 v192, v80
	v_exp_f32_e32 v193, v81
	v_exp_f32_e32 v194, v82
	s_waitcnt lgkmcnt(0)
	v_mfma_f32_32x32x16_bf16 v[64:79], v[172:175], v[116:119], v[64:79]
	v_exp_f32_e32 v207, v83
	v_exp_f32_e32 v208, v84
	v_exp_f32_e32 v209, v85
	v_exp_f32_e32 v210, v86
	v_mfma_f32_32x32x16_bf16 v[64:79], v[168:171], v[120:123], v[64:79]
	s_add_i32 s0, s57, 3
	v_exp_f32_e32 v211, v87
	s_cmp_lt_i32 s0, s45
	s_cselect_b32 s0, s0, s44
	s_add_i32 s1, s57, 2
	s_cmp_lt_i32 s57, s52
	s_cselect_b32 s48, s1, s44
	v_cvt_pk_bf16_f32 v80, v192, v193
	v_cvt_pk_bf16_f32 v81, v194, v207
	v_cvt_pk_bf16_f32 v82, v208, v209
	v_cvt_pk_bf16_f32 v83, v210, v211
	v_lshl_add_u32 v84, s58, 14, v206
	v_add_u32_e32 v212, 0x12000, v84
	v_add_u32_e32 v172, v212, v203
	ds_read_b128 v[84:87], v172
	ds_read_b128 v[164:167], v172 offset:4096
	ds_read_b128 v[168:171], v172 offset:8192
	ds_read_b128 v[172:175], v172 offset:12288
	v_add_f32_e32 v192, v193, v192
	v_add_f32_e32 v192, v194, v192
	v_add_f32_e32 v192, v207, v192
	v_add_f32_e32 v192, v208, v192
	v_add_f32_e32 v192, v209, v192
	v_add_f32_e32 v192, v210, v192
	v_add_f32_e32 v194, v211, v192
	s_mul_hi_u32 s1, s0, 0x6000
	s_mulk_i32 s0, 0x6000
	s_add_u32 s0, s92, s0
	s_mul_i32 s12, s58, 0x6000
	s_addc_u32 s1, s93, s1
	s_add_i32 s12, s71, s12
	v_lshl_add_u64 v[192:193], s[0:1], 0, v[182:183]
	s_mov_b32 m0, s12
	s_waitcnt lgkmcnt(5)
	v_mfma_f32_32x32x16_bf16 v[64:79], v[160:163], v[124:127], v[64:79]
	global_load_lds_dwordx4 v[192:193], off
	v_lshl_add_u64 v[192:193], s[0:1], 0, v[184:185]
	s_add_i32 m0, s12, 0x400
	s_nop 0
	global_load_lds_dwordx4 v[192:193], off
	v_lshl_add_u64 v[192:193], s[0:1], 0, v[186:187]
	s_add_i32 m0, s12, 0x800
	s_nop 0
	global_load_lds_dwordx4 v[192:193], off
	v_mfma_f32_32x32x16_bf16 v[64:79], v[148:151], v[128:131], v[64:79]
	v_exp_f32_e32 v88, v88
	v_exp_f32_e32 v89, v89
	v_exp_f32_e32 v90, v90
	v_mfma_f32_32x32x16_bf16 v[64:79], v[156:159], v[132:135], v[64:79]
	v_exp_f32_e32 v91, v91
	v_add_f32_e32 v148, v88, v194
	v_add_f32_e32 v148, v89, v148
	v_add_f32_e32 v148, v90, v148
	v_add_f32_e32 v156, v91, v148
	v_cvt_pk_bf16_f32 v88, v88, v89
	v_cvt_pk_bf16_f32 v89, v90, v91
	v_mfma_f32_32x32x16_bf16 v[64:79], v[152:155], v[136:139], v[64:79]
	s_waitcnt lgkmcnt(0)
	v_mfma_f32_32x32x16_bf16 v[64:79], v[144:147], v[140:143], v[64:79]
	s_lshl_b64 s[0:1], s[48:49], 7
	s_add_u32 s0, s94, s0
	s_addc_u32 s1, s95, s1
	s_lshl_b32 s12, s53, 14
	s_add_i32 s12, s12, 0
	s_add_i32 s12, s12, s68
	s_add_i32 m0, s12, 0x12000
	v_lshl_add_u64 v[90:91], s[0:1], 0, v[176:177]
	global_load_lds_dwordx4 v[90:91], off
	v_lshl_add_u64 v[90:91], s[0:1], 0, v[188:189]
	s_add_i32 m0, s12, 0x12400
	s_nop 0
	global_load_lds_dwordx4 v[90:91], off
	v_add_u32_e32 v90, v212, v204
	v_mfma_f32_32x32x16_bf16 v[48:63], v[84:87], v[80:83], v[48:63]
	ds_read_b128 v[84:87], v90
	ds_read_b128 v[144:147], v90 offset:4096
	ds_read_b128 v[148:151], v90 offset:8192
	ds_read_b128 v[152:155], v90 offset:12288
	v_exp_f32_e32 v90, v92
	v_exp_f32_e32 v91, v93
	v_exp_f32_e32 v92, v94
	v_mfma_f32_32x32x16_bf16 v[32:47], v[164:167], v[80:83], v[32:47]
	v_exp_f32_e32 v93, v95
	v_add_f32_e32 v94, v90, v156
	v_add_f32_e32 v94, v91, v94
	v_add_f32_e32 v94, v92, v94
	v_add_f32_e32 v94, v93, v94
	v_add_f32_e32 v180, v180, v94
	v_mfma_f32_32x32x16_bf16 v[16:31], v[168:171], v[80:83], v[16:31]
	v_cvt_pk_bf16_f32 v90, v90, v91
	v_cvt_pk_bf16_f32 v91, v92, v93
	v_mfma_f32_32x32x16_bf16 v[0:15], v[172:175], v[80:83], v[0:15]
	s_waitcnt lgkmcnt(0)
	v_mfma_f32_32x32x16_bf16 v[48:63], v[84:87], v[88:91], v[48:63]
	s_waitcnt vmcnt(5) lgkmcnt(0)
	s_barrier
	s_add_i32 s57, s57, 1
	s_add_i32 s56, s56, 64
	s_cmp_eq_u32 s45, s57
	v_mfma_f32_32x32x16_bf16 v[32:47], v[144:147], v[88:91], v[32:47]
	v_mfma_f32_32x32x16_bf16 v[16:31], v[148:151], v[88:91], v[16:31]
	v_mfma_f32_32x32x16_bf16 v[0:15], v[152:155], v[88:91], v[0:15]
	s_cbranch_scc1 .LBB0_495
	s_mov_b32 s0, s55
	s_mov_b32 s55, s53
	s_mov_b32 s53, s58
	s_add_i32 s1, s54, s56
	s_cmp_lt_i32 s1, 0
	s_mov_b32 s58, s0
	s_cbranch_scc0 .LBB0_488
	s_branch .LBB0_489
